# attention: packed -mhat-cb updates in PV gaps split into scalar v_sub pairs (plus barrier invalidate move)
# baseline (speedup 1.0000x reference)
.LBB0_1098:
	ds_read_b128 v[66:69], v190
	ds_read_b128 v[102:105], v190 offset:32
	ds_read_b128 v[106:109], v190 offset:64
	ds_read_b128 v[110:113], v190 offset:96
	ds_read_b128 v[192:195], v190 offset:128
	ds_read_b128 v[70:73], v190 offset:160
	ds_read_b128 v[74:77], v190 offset:192
	ds_read_b128 v[78:81], v190 offset:224
	s_waitcnt lgkmcnt(14)
	v_mfma_f32_32x32x16_bf16 v[34:49], v[142:145], v[182:185], v[34:49]
	v_exp_f32_e32 v82, v82
	v_exp_f32_e32 v83, v83
	v_exp_f32_e32 v84, v84
	v_exp_f32_e32 v85, v85
	s_waitcnt lgkmcnt(7)
	v_sub_f32_e64 v98, -v200, v66
	v_sub_f32_e64 v99, -v200, v67
	v_sub_f32_e64 v100, -v200, v68
	v_sub_f32_e64 v101, -v200, v69
	s_waitcnt lgkmcnt(4)
	v_mfma_f32_32x32x16_bf16 v[18:33], v[142:145], v[178:181], v[18:33]
	v_exp_f32_e32 v86, v86
	v_exp_f32_e32 v87, v87
	v_exp_f32_e32 v88, v88
	v_exp_f32_e32 v89, v89
	v_sub_f32_e64 v102, -v200, v102
	v_sub_f32_e64 v103, -v200, v103
	v_sub_f32_e64 v104, -v200, v104
	v_sub_f32_e64 v105, -v200, v105
	v_add_u32_e32 v16, s74, v231
	ds_read_b128 v[162:165], v16
	ds_read_b128 v[150:153], v16 offset:512
	v_mfma_f32_32x32x16_bf16 v[34:49], v[138:141], v[174:177], v[34:49]
	v_exp_f32_e32 v90, v90
	v_exp_f32_e32 v91, v91
	v_exp_f32_e32 v92, v92
	v_exp_f32_e32 v93, v93
	v_sub_f32_e64 v106, -v200, v106
	v_sub_f32_e64 v107, -v200, v107
	v_sub_f32_e64 v108, -v200, v108
	v_sub_f32_e64 v109, -v200, v109
	ds_read_b128 v[170:173], v16 offset:2048
	ds_read_b128 v[146:149], v16 offset:2560
	v_mfma_f32_32x32x16_bf16 v[18:33], v[138:141], v[166:169], v[18:33]
	v_exp_f32_e32 v94, v94
	v_exp_f32_e32 v95, v95
	v_exp_f32_e32 v96, v96
	v_exp_f32_e32 v97, v97
	v_sub_f32_e64 v110, -v200, v110
	v_sub_f32_e64 v111, -v200, v111
	v_sub_f32_e64 v112, -v200, v112
	v_sub_f32_e64 v113, -v200, v113
	ds_read_b128 v[166:169], v16 offset:4096
	ds_read_b128 v[154:157], v16 offset:4608
	v_mfma_f32_32x32x16_bf16 v[34:49], v[134:137], v[158:161], v[34:49]
	v_exp_f32_e32 v50, v50
	v_exp_f32_e32 v51, v51
	v_exp_f32_e32 v52, v52
	v_exp_f32_e32 v53, v53
	s_waitcnt lgkmcnt(9)
	v_sub_f32_e64 v66, -v200, v192
	v_sub_f32_e64 v67, -v200, v193
	v_sub_f32_e64 v68, -v200, v194
	v_sub_f32_e64 v69, -v200, v195
	s_waitcnt lgkmcnt(6)
	ds_read_b128 v[174:177], v16 offset:6144
	ds_read_b128 v[158:161], v16 offset:6656
	v_mfma_f32_32x32x16_bf16 v[18:33], v[134:137], v[12:15], v[18:33]
	v_exp_f32_e32 v54, v54
	v_exp_f32_e32 v55, v55
	v_exp_f32_e32 v56, v56
	v_exp_f32_e32 v57, v57
	v_sub_f32_e64 v70, -v200, v70
	v_sub_f32_e64 v71, -v200, v71
	v_sub_f32_e64 v72, -v200, v72
	v_sub_f32_e64 v73, -v200, v73
	v_mfma_f32_32x32x16_bf16 v[34:49], v[122:125], v[8:11], v[34:49]
	v_exp_f32_e32 v58, v58
	v_exp_f32_e32 v59, v59
	v_exp_f32_e32 v60, v60
	v_exp_f32_e32 v61, v61
	v_sub_f32_e64 v74, -v200, v74
	v_sub_f32_e64 v75, -v200, v75
	v_sub_f32_e64 v76, -v200, v76
	v_sub_f32_e64 v77, -v200, v77
	v_mfma_f32_32x32x16_bf16 v[18:33], v[122:125], v[4:7], v[18:33]
	v_exp_f32_e32 v62, v62
	v_exp_f32_e32 v63, v63
	v_exp_f32_e32 v64, v64
	v_exp_f32_e32 v65, v65
	v_sub_f32_e64 v78, -v200, v78
	v_sub_f32_e64 v79, -v200, v79
	v_sub_f32_e64 v80, -v200, v80
	v_sub_f32_e64 v81, -v200, v81
	s_waitcnt vmcnt(2) lgkmcnt(0)
	s_barrier
	s_andn2_b64 vcc, exec, s[70:71]
	s_cbranch_vccnz .LBB0_1100
	s_waitcnt lgkmcnt(0)
	ds_read_b128 v[4:7], v227 offset:49248
	ds_read_b128 v[8:11], v227 offset:49216
	ds_read_b128 v[12:15], v227 offset:49184
	ds_read_b128 v[178:181], v227 offset:49152
	s_waitcnt lgkmcnt(3)
	v_pk_mul_f32 v[48:49], v[48:49], v[6:7]
	s_waitcnt lgkmcnt(2)
	v_pk_mul_f32 v[44:45], v[44:45], v[10:11]
	s_waitcnt lgkmcnt(1)
	v_pk_mul_f32 v[40:41], v[40:41], v[14:15]
	s_waitcnt lgkmcnt(0)
	v_pk_mul_f32 v[36:37], v[36:37], v[180:181]
	v_pk_mul_f32 v[46:47], v[46:47], v[4:5]
	v_pk_mul_f32 v[42:43], v[42:43], v[8:9]
	v_pk_mul_f32 v[38:39], v[38:39], v[12:13]
	v_pk_mul_f32 v[34:35], v[34:35], v[178:179]
	v_pk_mul_f32 v[32:33], v[32:33], v[6:7]
	v_pk_mul_f32 v[28:29], v[28:29], v[10:11]
	v_pk_mul_f32 v[24:25], v[24:25], v[14:15]
	v_pk_mul_f32 v[20:21], v[20:21], v[180:181]
	v_pk_mul_f32 v[30:31], v[30:31], v[4:5]
	v_pk_mul_f32 v[26:27], v[26:27], v[8:9]
	v_pk_mul_f32 v[22:23], v[22:23], v[12:13]
	v_pk_mul_f32 v[18:19], v[18:19], v[178:179]

.LBB0_1101:
	ds_read_b128 v[50:53], v190 offset:256
	ds_read_b128 v[86:89], v190 offset:288
	ds_read_b128 v[90:93], v190 offset:320
	ds_read_b128 v[94:97], v190 offset:352
	ds_read_b128 v[154:157], v190 offset:384
	ds_read_b128 v[54:57], v190 offset:416
	ds_read_b128 v[58:61], v190 offset:448
	ds_read_b128 v[62:65], v190 offset:480
	s_waitcnt lgkmcnt(14)
	v_mfma_f32_32x32x16_bf16 v[34:49], v[142:145], v[182:185], v[34:49]
	v_exp_f32_e32 v98, v98
	v_exp_f32_e32 v99, v99
	v_exp_f32_e32 v100, v100
	v_exp_f32_e32 v101, v101
	s_waitcnt lgkmcnt(7)
	v_sub_f32_e64 v82, -v200, v50
	v_sub_f32_e64 v83, -v200, v51
	v_sub_f32_e64 v84, -v200, v52
	v_sub_f32_e64 v85, -v200, v53
	s_waitcnt lgkmcnt(4)
	v_mfma_f32_32x32x16_bf16 v[18:33], v[142:145], v[178:181], v[18:33]
	v_exp_f32_e32 v102, v102
	v_exp_f32_e32 v103, v103
	v_exp_f32_e32 v104, v104
	v_exp_f32_e32 v105, v105
	v_sub_f32_e64 v86, -v200, v86
	v_sub_f32_e64 v87, -v200, v87
	v_sub_f32_e64 v88, -v200, v88
	v_sub_f32_e64 v89, -v200, v89
	v_add_u32_e32 v2, s87, v231
	ds_read_b128 v[174:177], v2
	ds_read_b128 v[166:169], v2 offset:512
	v_mfma_f32_32x32x16_bf16 v[34:49], v[138:141], v[162:165], v[34:49]
	v_exp_f32_e32 v106, v106
	v_exp_f32_e32 v107, v107
	v_exp_f32_e32 v108, v108
	v_exp_f32_e32 v109, v109
	v_sub_f32_e64 v90, -v200, v90
	v_sub_f32_e64 v91, -v200, v91
	v_sub_f32_e64 v92, -v200, v92
	v_sub_f32_e64 v93, -v200, v93
	ds_read_b128 v[170:173], v2 offset:2048
	ds_read_b128 v[158:161], v2 offset:2560
	v_mfma_f32_32x32x16_bf16 v[18:33], v[138:141], v[150:153], v[18:33]
	v_exp_f32_e32 v110, v110
	v_exp_f32_e32 v111, v111
	v_exp_f32_e32 v112, v112
	v_exp_f32_e32 v113, v113
	v_sub_f32_e64 v94, -v200, v94
	v_sub_f32_e64 v95, -v200, v95
	v_sub_f32_e64 v96, -v200, v96
	v_sub_f32_e64 v97, -v200, v97
	ds_read_b128 v[162:165], v2 offset:4096
	ds_read_b128 v[150:153], v2 offset:4608
	v_mfma_f32_32x32x16_bf16 v[34:49], v[134:137], v[146:149], v[34:49]
	v_exp_f32_e32 v66, v66
	v_exp_f32_e32 v67, v67
	v_exp_f32_e32 v68, v68
	v_exp_f32_e32 v69, v69
	s_waitcnt lgkmcnt(9)
	v_sub_f32_e64 v50, -v200, v154
	v_sub_f32_e64 v51, -v200, v155
	v_sub_f32_e64 v52, -v200, v156
	v_sub_f32_e64 v53, -v200, v157
	s_waitcnt lgkmcnt(6)
	ds_read_b128 v[154:157], v2 offset:6144
	ds_read_b128 v[146:149], v2 offset:6656
	v_mfma_f32_32x32x16_bf16 v[18:33], v[134:137], v[12:15], v[18:33]
	v_exp_f32_e32 v70, v70
	v_exp_f32_e32 v71, v71
	v_exp_f32_e32 v72, v72
	v_exp_f32_e32 v73, v73
	v_sub_f32_e64 v54, -v200, v54
	v_sub_f32_e64 v55, -v200, v55
	v_sub_f32_e64 v56, -v200, v56
	v_sub_f32_e64 v57, -v200, v57
	v_mfma_f32_32x32x16_bf16 v[34:49], v[122:125], v[8:11], v[34:49]
	v_exp_f32_e32 v74, v74
	v_exp_f32_e32 v75, v75
	v_exp_f32_e32 v76, v76
	v_exp_f32_e32 v77, v77
	v_sub_f32_e64 v58, -v200, v58
	v_sub_f32_e64 v59, -v200, v59
	v_sub_f32_e64 v60, -v200, v60
	v_sub_f32_e64 v61, -v200, v61
	v_mfma_f32_32x32x16_bf16 v[18:33], v[122:125], v[4:7], v[18:33]
	v_exp_f32_e32 v78, v78
	v_exp_f32_e32 v79, v79
	v_exp_f32_e32 v80, v80
	v_exp_f32_e32 v81, v81
	v_sub_f32_e64 v62, -v200, v62
	v_sub_f32_e64 v63, -v200, v63
	v_sub_f32_e64 v64, -v200, v64
	v_sub_f32_e64 v65, -v200, v65
	s_waitcnt vmcnt(2) lgkmcnt(0)
	s_barrier
	s_andn2_b64 vcc, exec, s[70:71]
	s_cbranch_vccnz .LBB0_1103
	s_waitcnt lgkmcnt(0)
	ds_read_b128 v[4:7], v227 offset:49248
	ds_read_b128 v[8:11], v227 offset:49216
	ds_read_b128 v[12:15], v227 offset:49184
	ds_read_b128 v[178:181], v227 offset:49152
	s_waitcnt lgkmcnt(3)
	v_pk_mul_f32 v[48:49], v[48:49], v[6:7]
	s_waitcnt lgkmcnt(2)
	v_pk_mul_f32 v[44:45], v[44:45], v[10:11]
	s_waitcnt lgkmcnt(1)
	v_pk_mul_f32 v[40:41], v[40:41], v[14:15]
	s_waitcnt lgkmcnt(0)
	v_pk_mul_f32 v[36:37], v[36:37], v[180:181]
	v_pk_mul_f32 v[46:47], v[46:47], v[4:5]
	v_pk_mul_f32 v[42:43], v[42:43], v[8:9]
	v_pk_mul_f32 v[38:39], v[38:39], v[12:13]
	v_pk_mul_f32 v[34:35], v[34:35], v[178:179]
	v_pk_mul_f32 v[32:33], v[32:33], v[6:7]
	v_pk_mul_f32 v[28:29], v[28:29], v[10:11]
	v_pk_mul_f32 v[24:25], v[24:25], v[14:15]
	v_pk_mul_f32 v[20:21], v[20:21], v[180:181]
	v_pk_mul_f32 v[30:31], v[30:31], v[4:5]
	v_pk_mul_f32 v[26:27], v[26:27], v[8:9]
	v_pk_mul_f32 v[22:23], v[22:23], v[12:13]
	v_pk_mul_f32 v[18:19], v[18:19], v[178:179]

.LBB0_1118:
	s_lshl_b32 s28, s84, 8
	s_add_i32 s83, s83, s28
	v_lshl_add_u32 v17, v224, 2, s83
	ds_read_b128 v[82:85], v17
	ds_read_b128 v[102:105], v17 offset:32
	ds_read_b128 v[106:109], v17 offset:64
	ds_read_b128 v[110:113], v17 offset:96
	ds_read_b128 v[114:117], v17 offset:128
	ds_read_b128 v[86:89], v17 offset:160
	ds_read_b128 v[90:93], v17 offset:192
	ds_read_b128 v[94:97], v17 offset:224
	s_waitcnt lgkmcnt(14)
	v_mfma_f32_32x32x16_bf16 v[34:49], v[142:145], v[178:181], v[34:49]
	v_exp_f32_e32 v66, v66
	v_exp_f32_e32 v67, v67
	v_exp_f32_e32 v68, v68
	v_exp_f32_e32 v69, v69
	s_waitcnt lgkmcnt(7)
	v_sub_f32_e64 v98, -v200, v82
	v_sub_f32_e64 v99, -v200, v83
	v_sub_f32_e64 v100, -v200, v84
	v_sub_f32_e64 v101, -v200, v85
	s_waitcnt lgkmcnt(4)
	v_mfma_f32_32x32x16_bf16 v[18:33], v[142:145], v[174:177], v[18:33]
	v_exp_f32_e32 v70, v70
	v_exp_f32_e32 v71, v71
	v_exp_f32_e32 v72, v72
	v_exp_f32_e32 v73, v73
	v_sub_f32_e64 v102, -v200, v102
	v_sub_f32_e64 v103, -v200, v103
	v_sub_f32_e64 v104, -v200, v104
	v_sub_f32_e64 v105, -v200, v105
	v_mfma_f32_32x32x16_bf16 v[34:49], v[138:141], v[166:169], v[34:49]
	v_exp_f32_e32 v74, v74
	v_exp_f32_e32 v75, v75
	v_exp_f32_e32 v76, v76
	v_exp_f32_e32 v77, v77
	v_sub_f32_e64 v106, -v200, v106
	v_sub_f32_e64 v107, -v200, v107
	v_sub_f32_e64 v108, -v200, v108
	v_sub_f32_e64 v109, -v200, v109
	v_mfma_f32_32x32x16_bf16 v[18:33], v[138:141], v[130:133], v[18:33]
	v_exp_f32_e32 v78, v78
	v_exp_f32_e32 v79, v79
	v_exp_f32_e32 v80, v80
	v_exp_f32_e32 v81, v81
	v_sub_f32_e64 v110, -v200, v110
	v_sub_f32_e64 v111, -v200, v111
	v_sub_f32_e64 v112, -v200, v112
	v_sub_f32_e64 v113, -v200, v113
	v_mfma_f32_32x32x16_bf16 v[34:49], v[134:137], v[126:129], v[34:49]
	v_exp_f32_e32 v50, v50
	v_exp_f32_e32 v51, v51
	v_exp_f32_e32 v52, v52
	v_exp_f32_e32 v53, v53
	s_waitcnt lgkmcnt(3)
	v_sub_f32_e64 v82, -v200, v114
	v_sub_f32_e64 v83, -v200, v115
	v_sub_f32_e64 v84, -v200, v116
	v_sub_f32_e64 v85, -v200, v117
	s_waitcnt lgkmcnt(0)
	v_mfma_f32_32x32x16_bf16 v[18:33], v[134:137], v[12:15], v[18:33]
	v_exp_f32_e32 v54, v54
	v_exp_f32_e32 v55, v55
	v_exp_f32_e32 v56, v56
	v_exp_f32_e32 v57, v57
	v_sub_f32_e64 v86, -v200, v86
	v_sub_f32_e64 v87, -v200, v87
	v_sub_f32_e64 v88, -v200, v88
	v_sub_f32_e64 v89, -v200, v89
	v_mfma_f32_32x32x16_bf16 v[34:49], v[122:125], v[8:11], v[34:49]
	v_exp_f32_e32 v58, v58
	v_exp_f32_e32 v59, v59
	v_exp_f32_e32 v60, v60
	v_exp_f32_e32 v61, v61
	v_sub_f32_e64 v90, -v200, v90
	v_sub_f32_e64 v91, -v200, v91
	v_sub_f32_e64 v92, -v200, v92
	v_sub_f32_e64 v93, -v200, v93
	v_mfma_f32_32x32x16_bf16 v[18:33], v[122:125], v[4:7], v[18:33]
	v_exp_f32_e32 v62, v62
	v_exp_f32_e32 v63, v63
	v_exp_f32_e32 v64, v64
	v_exp_f32_e32 v65, v65
	v_sub_f32_e64 v94, -v200, v94
	v_sub_f32_e64 v95, -v200, v95
	v_sub_f32_e64 v96, -v200, v96
	v_sub_f32_e64 v97, -v200, v97
	s_andn2_b64 vcc, exec, s[24:25]
	s_cbranch_vccnz .LBB0_1120
	s_waitcnt lgkmcnt(0)
	ds_read_b128 v[4:7], v227 offset:49248
	ds_read_b128 v[8:11], v227 offset:49216
	ds_read_b128 v[12:15], v227 offset:49184
	ds_read_b128 v[82:85], v227 offset:49152
	s_waitcnt lgkmcnt(3)
	v_pk_mul_f32 v[48:49], v[48:49], v[6:7]
	s_waitcnt lgkmcnt(2)
	v_pk_mul_f32 v[44:45], v[44:45], v[10:11]
	s_waitcnt lgkmcnt(1)
	v_pk_mul_f32 v[40:41], v[40:41], v[14:15]
	s_waitcnt lgkmcnt(0)
	v_pk_mul_f32 v[36:37], v[36:37], v[84:85]
	v_pk_mul_f32 v[46:47], v[46:47], v[4:5]
	v_pk_mul_f32 v[42:43], v[42:43], v[8:9]
	v_pk_mul_f32 v[38:39], v[38:39], v[12:13]
	v_pk_mul_f32 v[34:35], v[34:35], v[82:83]
	v_pk_mul_f32 v[32:33], v[32:33], v[6:7]
	v_pk_mul_f32 v[28:29], v[28:29], v[10:11]
	v_pk_mul_f32 v[24:25], v[24:25], v[14:15]
	v_pk_mul_f32 v[20:21], v[20:21], v[84:85]
	v_pk_mul_f32 v[30:31], v[30:31], v[4:5]
	v_pk_mul_f32 v[26:27], v[26:27], v[8:9]
	v_pk_mul_f32 v[22:23], v[22:23], v[12:13]
	v_pk_mul_f32 v[18:19], v[18:19], v[82:83]

.LBB0_1131:
	ds_read_b128 v[66:69], v234
	ds_read_b128 v[102:105], v234 offset:32
	ds_read_b128 v[106:109], v234 offset:64
	ds_read_b128 v[110:113], v234 offset:96
	ds_read_b128 v[146:149], v234 offset:128
	ds_read_b128 v[70:73], v234 offset:160
	ds_read_b128 v[74:77], v234 offset:192
	ds_read_b128 v[78:81], v234 offset:224
	s_waitcnt lgkmcnt(14)
	v_mfma_f32_32x32x16_bf16 v[34:49], v[142:145], v[190:193], v[34:49]
	v_exp_f32_e32 v82, v82
	v_exp_f32_e32 v83, v83
	v_exp_f32_e32 v84, v84
	v_exp_f32_e32 v85, v85
	s_waitcnt lgkmcnt(7)
	v_sub_f32_e64 v98, -v200, v66
	v_sub_f32_e64 v99, -v200, v67
	v_sub_f32_e64 v100, -v200, v68
	v_sub_f32_e64 v101, -v200, v69
	s_waitcnt lgkmcnt(4)
	v_mfma_f32_32x32x16_bf16 v[18:33], v[142:145], v[174:177], v[18:33]
	v_exp_f32_e32 v86, v86
	v_exp_f32_e32 v87, v87
	v_exp_f32_e32 v88, v88
	v_exp_f32_e32 v89, v89
	v_sub_f32_e64 v102, -v200, v102
	v_sub_f32_e64 v103, -v200, v103
	v_sub_f32_e64 v104, -v200, v104
	v_sub_f32_e64 v105, -v200, v105
	v_add_u32_e32 v17, s88, v231
	ds_read_b128 v[174:177], v17
	ds_read_b128 v[166:169], v17 offset:512
	v_mfma_f32_32x32x16_bf16 v[34:49], v[138:141], v[186:189], v[34:49]
	v_exp_f32_e32 v90, v90
	v_exp_f32_e32 v91, v91
	v_exp_f32_e32 v92, v92
	v_exp_f32_e32 v93, v93
	v_sub_f32_e64 v106, -v200, v106
	v_sub_f32_e64 v107, -v200, v107
	v_sub_f32_e64 v108, -v200, v108
	v_sub_f32_e64 v109, -v200, v109
	ds_read_b128 v[170:173], v17 offset:2048
	ds_read_b128 v[158:161], v17 offset:2560
	v_mfma_f32_32x32x16_bf16 v[18:33], v[138:141], v[182:185], v[18:33]
	v_exp_f32_e32 v94, v94
	v_exp_f32_e32 v95, v95
	v_exp_f32_e32 v96, v96
	v_exp_f32_e32 v97, v97
	v_sub_f32_e64 v110, -v200, v110
	v_sub_f32_e64 v111, -v200, v111
	v_sub_f32_e64 v112, -v200, v112
	v_sub_f32_e64 v113, -v200, v113
	ds_read_b128 v[162:165], v17 offset:4096
	ds_read_b128 v[150:153], v17 offset:4608
	v_mfma_f32_32x32x16_bf16 v[34:49], v[134:137], v[178:181], v[34:49]
	v_exp_f32_e32 v50, v50
	v_exp_f32_e32 v51, v51
	v_exp_f32_e32 v52, v52
	v_exp_f32_e32 v53, v53
	s_waitcnt lgkmcnt(9)
	v_sub_f32_e64 v66, -v200, v146
	v_sub_f32_e64 v67, -v200, v147
	v_sub_f32_e64 v68, -v200, v148
	v_sub_f32_e64 v69, -v200, v149
	s_waitcnt lgkmcnt(6)
	ds_read_b128 v[154:157], v17 offset:6144
	ds_read_b128 v[146:149], v17 offset:6656
	v_mfma_f32_32x32x16_bf16 v[18:33], v[134:137], v[12:15], v[18:33]
	v_exp_f32_e32 v54, v54
	v_exp_f32_e32 v55, v55
	v_exp_f32_e32 v56, v56
	v_exp_f32_e32 v57, v57
	v_sub_f32_e64 v70, -v200, v70
	v_sub_f32_e64 v71, -v200, v71
	v_sub_f32_e64 v72, -v200, v72
	v_sub_f32_e64 v73, -v200, v73
	v_mfma_f32_32x32x16_bf16 v[34:49], v[122:125], v[8:11], v[34:49]
	v_exp_f32_e32 v58, v58
	v_exp_f32_e32 v59, v59
	v_exp_f32_e32 v60, v60
	v_exp_f32_e32 v61, v61
	v_sub_f32_e64 v74, -v200, v74
	v_sub_f32_e64 v75, -v200, v75
	v_sub_f32_e64 v76, -v200, v76
	v_sub_f32_e64 v77, -v200, v77
	v_mfma_f32_32x32x16_bf16 v[18:33], v[122:125], v[4:7], v[18:33]
	v_exp_f32_e32 v62, v62
	v_exp_f32_e32 v63, v63
	v_exp_f32_e32 v64, v64
	v_exp_f32_e32 v65, v65
	v_sub_f32_e64 v78, -v200, v78
	v_sub_f32_e64 v79, -v200, v79
	v_sub_f32_e64 v80, -v200, v80
	v_sub_f32_e64 v81, -v200, v81
	s_mov_b64 s[74:75], -1
	s_and_b64 vcc, exec, s[70:71]
	s_cbranch_vccz .LBB0_1164
	s_cmp_ge_i32 s24, s84
	s_cbranch_scc0 .LBB0_1134
	s_waitcnt vmcnt(0) lgkmcnt(0)
	s_barrier
	s_mov_b64 s[74:75], 0

.LBB0_1146:
	ds_read_b128 v[82:85], v234 offset:256
	ds_read_b128 v[86:89], v234 offset:288
	ds_read_b128 v[90:93], v234 offset:320
	ds_read_b128 v[94:97], v234 offset:352
	ds_read_b128 v[50:53], v234 offset:384
	ds_read_b128 v[54:57], v234 offset:416
	ds_read_b128 v[58:61], v234 offset:448
	ds_read_b128 v[62:65], v234 offset:480
	s_waitcnt lgkmcnt(14)
	v_mfma_f32_32x32x16_bf16 v[34:49], v[142:145], v[194:197], v[34:49]
	v_exp_f32_e32 v98, v98
	v_exp_f32_e32 v99, v99
	v_exp_f32_e32 v100, v100
	v_exp_f32_e32 v101, v101
	s_waitcnt lgkmcnt(7)
	v_sub_f32_e64 v82, -v200, v82
	v_sub_f32_e64 v83, -v200, v83
	v_sub_f32_e64 v84, -v200, v84
	v_sub_f32_e64 v85, -v200, v85
	s_waitcnt lgkmcnt(4)
	v_mfma_f32_32x32x16_bf16 v[18:33], v[142:145], v[190:193], v[18:33]
	v_exp_f32_e32 v102, v102
	v_exp_f32_e32 v103, v103
	v_exp_f32_e32 v104, v104
	v_exp_f32_e32 v105, v105
	v_sub_f32_e64 v86, -v200, v86
	v_sub_f32_e64 v87, -v200, v87
	v_sub_f32_e64 v88, -v200, v88
	v_sub_f32_e64 v89, -v200, v89
	v_cndmask_b32_e64 v16, 0, 1, s[76:77]
	v_cmp_ne_u32_e64 s[24:25], 1, v16
	s_andn2_b64 vcc, exec, s[76:77]
	v_add_u32_e32 v142, s87, v231
	s_cbranch_vccnz .LBB0_1148
	ds_read_b128 v[174:177], v142
	ds_read_b128 v[166:169], v142 offset:512
